# v16: v9 + norm gain-vector loads hoisted + relu max pairs folded + GEMM static priority for waves 4-7 (per-phase flips removed)
# speedup vs baseline: 1.0143x; 1.0143x over previous
; DI int opaque_tid() { int t = threadIdx.x; asm volatile("" : "+v"(t)); return t; }
; DI int opaque_s(int t) { asm volatile("" : "+s"(t)); return t; }
; DI float wave_sum(float v) { for (int o = 32; o >= 1; o >>= 1) v += __shfl_xor(v, o); return v; }
; DI f32x2 unh2(unsigned w) { return __builtin_convertvector(__builtin_bit_cast(h2_t, w), f32x2); }
;     const int tid_ = opaque_tid(); const int lane = tid_ & 63, gw = opaque_s(blockIdx.x) * 8 + (tid_ >> 6), nw = opaque_s(gridDim.x) * 8;
;     const float* ssq_t = (const float*)(P.ws + WS_SSQT);
;     bf16_t* pb = (bf16_t*)(P.ws + A_PB);
;     unsigned short* X16 = (unsigned short*)(P.ws + A_H);
;     constexpr int RU = 2;
;     for (int row0 = gw; row0 < MTOK; row0 += RU * nw) {
;         f32x4 xv[RU][4]; u32x2 tw[RU][4]; float sq[RU]; f32x4 pv[RU];
; #pragma unroll
;         for (int r = 0; r < RU; ++r) { const int rrow = row0 + r * nw; const int row = rev ? MTOK - 1 - rrow : rrow; if (rrow < MTOK) {
;             if (mode == 0) { const float* xs = row < NPROMPT ? P.in[0] + (size_t)row * 1024 : P.in[1] + (size_t)(row - NPROMPT) * 1024;
; #pragma unroll
;                 for (int i = 0; i < 4; ++i) xv[r][i] = *(const f32x4*)(xs + (i * 64 + lane) * 4);
;             } else {
; #pragma unroll
;                 for (int i = 0; i < 4; ++i) { const u32x2 xw = __builtin_nontemporal_load((const u32x2*)(X16 + (size_t)row * 1024 + (i * 64 + lane) * 4)); const f32x2 a = unh2(xw.x), c = unh2(xw.y); xv[r][i] = (f32x4){a.x, a.y, c.x, c.y}; }
;                 sq[r] = lane < 16 ? ssq_t[row * 16 + lane] : 0.f;
; #pragma unroll
;                 for (int i = 0; i < 4; ++i) tw[r][i] = __builtin_nontemporal_load((const u32x2*)(T + (size_t)row * 1024 + (i * 64 + lane) * 4)); }
;             if (mode == 2) { const float* pp = row < NPROMPT ? P.in[2] + ((size_t)layer * NPROMPT + row) * 256 : P.in[3] + ((size_t)layer * (MTOK - NPROMPT) + (row - NPROMPT)) * 256;
;                 pv[r] = *(const f32x4*)(pp + lane * 4); } } }
; #pragma unroll
;         for (int r = 0; r < RU; ++r) { const int rrow = row0 + r * nw; const int row = rev ? MTOK - 1 - rrow : rrow; if (rrow < MTOK) {
;             if (mode != 0) { const float rs = rsqrtf(wave_sum(sq[r]) * (1.0f / 1024.0f) + EPSN);
; #pragma unroll
;                 for (int i = 0; i < 4; ++i) { const f32x4 g4 = *(const f32x4*)(gain + (i * 64 + lane) * 4);
.LBB0_1303:
	s_or_b64 exec, exec, s[2:3]
	v_mov_b32_e32 v1, v164
	v_readlane_b32 s0, v238, 0
	s_waitcnt lgkmcnt(0)
	s_barrier
	s_lshl_b32 s0, s0, 3
	v_ashrrev_i32_e32 v0, 6, v1
	v_readlane_b32 s2, v236, 41
	v_add_u32_e32 v64, s0, v0
	v_readlane_b32 s3, v236, 42
	s_lshl_b32 s8, s2, 10
	s_mov_b32 s4, s52
	v_cmp_gt_i32_e32 vcc, s56, v64
	v_and_b32_e32 v148, 64, v184
	v_xor_b32_e32 v147, 32, v184
	v_xor_b32_e32 v146, 16, v184
	v_xor_b32_e32 v145, 8, v184
	v_xor_b32_e32 v144, 4, v184
	v_xor_b32_e32 v143, 2, v184
	v_xor_b32_e32 v142, 1, v184
	s_and_saveexec_b64 s[2:3], vcc
	s_cbranch_execz .LBB0_1314
	v_and_b32_e32 v65, 63, v1
	v_add_u32_e32 v1, 64, v148
	v_cmp_lt_i32_e64 s[38:39], v147, v1
	s_lshl_b32 s16, s4, 3
	s_lshl_b64 s[10:11], s[8:9], 2
	v_cndmask_b32_e64 v2, v184, v147, s[38:39]
	v_cmp_lt_i32_e64 s[38:39], v146, v1
	v_lshlrev_b32_e32 v66, 2, v2
	s_add_u32 s10, s48, s10
	v_cndmask_b32_e64 v2, v184, v146, s[38:39]
	v_cmp_lt_i32_e64 s[38:39], v145, v1
	v_lshlrev_b32_e32 v67, 2, v2
	s_addc_u32 s11, s49, s11
	v_cndmask_b32_e64 v2, v184, v145, s[38:39]
	v_cmp_lt_i32_e64 s[38:39], v144, v1
	v_lshlrev_b32_e32 v68, 2, v2
	s_lshl_b32 s17, s4, 4
	v_cndmask_b32_e64 v2, v184, v144, s[38:39]
	v_cmp_lt_i32_e64 s[38:39], v143, v1
	v_lshlrev_b32_e32 v166, 4, v65
	v_lshlrev_b32_e32 v69, 2, v2
	v_cndmask_b32_e64 v2, v184, v143, s[38:39]
	v_cmp_lt_i32_e64 s[38:39], v142, v1
	v_readlane_b32 s4, v238, 19
	v_lshl_add_u64 v[4:5], s[10:11], 0, v[166:167]
	global_load_dwordx4 v[240:243], v[4:5], off
	global_load_dwordx4 v[244:247], v[4:5], off offset:1024
	global_load_dwordx4 v[248:251], v[4:5], off offset:2048
	global_load_dwordx4 v[252:255], v[4:5], off offset:3072
	v_cndmask_b32_e64 v1, v184, v142, s[38:39]
	v_lshlrev_b32_e32 v166, 3, v65
	v_readlane_b32 s5, v238, 20
	v_readlane_b32 s36, v238, 1
	v_readlane_b32 s42, v238, 7
	v_lshl_add_u64 v[6:7], s[4:5], 0, v[166:167]
	v_readlane_b32 s4, v237, 44
	v_readlane_b32 s43, v238, 8
	v_readlane_b32 s46, v238, 11
	v_readlane_b32 s47, v238, 12
	v_readlane_b32 s5, v237, 45
	v_readlane_b32 s48, v238, 13
	v_readlane_b32 s49, v238, 14
	v_readlane_b32 s46, v238, 30
	v_readlane_b32 s42, v236, 23
	v_add_u32_e32 v0, s0, v0
	v_cmp_gt_u32_e32 vcc, 16, v65
	v_lshlrev_b32_e32 v70, 2, v2
	v_lshlrev_b32_e32 v71, 2, v1
	v_lshl_add_u64 v[8:9], s[4:5], 0, v[166:167]
	v_readlane_b32 s47, v238, 31
	v_readlane_b32 s43, v236, 24
	v_readlane_b32 s33, v236, 20
	v_lshl_add_u64 v[10:11], s[48:49], 0, v[166:167]
	s_sub_i32 s18, 0, s16
	v_sub_u32_e32 v72, 0xbfff, v0
	s_mov_b64 s[10:11], 0
	v_mov_b64_e32 v[12:13], v[166:167]
	v_readlane_b32 s37, v238, 2
	v_readlane_b32 s38, v238, 3
	v_readlane_b32 s39, v238, 4
	v_readlane_b32 s40, v238, 5
	v_readlane_b32 s41, v238, 6
	v_readlane_b32 s44, v238, 9
	v_readlane_b32 s45, v238, 10
	v_readlane_b32 s50, v238, 15
	v_readlane_b32 s51, v238, 16
	s_branch .LBB0_1306

; DI unsigned pk2(float a, float b) { f32x2 v = {a, b}; return __builtin_bit_cast(unsigned, __builtin_convertvector(v, bf2_t)); }
; DI float blo(unsigned w) { return __uint_as_float(w << 16); }
; DI float bhi(unsigned w) { return __uint_as_float(w & 0xffff0000u); }
; DI float wave_sum(float v) { for (int o = 32; o >= 1; o >>= 1) v += __shfl_xor(v, o); return v; }
; DI unsigned pkh2(float a, float b) { f32x2 v = {a, b}; return __builtin_bit_cast(unsigned, __builtin_convertvector(v, h2_t)); }
;     ...
;         for (int r = 0; r < RU; ++r) { const int rrow = row0 + r * nw; const int row = rev ? MTOK - 1 - rrow : rrow; if (rrow < MTOK) {
;             if (mode != 0) { const float rs = rsqrtf(wave_sum(sq[r]) * (1.0f / 1024.0f) + EPSN);
; #pragma unroll
;                 for (int i = 0; i < 4; ++i) { const f32x4 g4 = *(const f32x4*)(gain + (i * 64 + lane) * 4);
;                     xv[r][i][0] += blo(tw[r][i].x) * rs * g4[0]; xv[r][i][1] += bhi(tw[r][i].x) * rs * g4[1]; xv[r][i][2] += blo(tw[r][i].y) * rs * g4[2]; xv[r][i][3] += bhi(tw[r][i].y) * rs * g4[3]; } }
;             if (fin) {
; #pragma unroll
;                 for (int i = 0; i < 4; ++i) *(f32x4*)(P.out + (size_t)row * 1024 + (i * 64 + lane) * 4) = xv[r][i];
;             } else {
;                 float ss = 0.f;
; #pragma unroll
;                 for (int i = 0; i < 4; ++i) ss += xv[r][i][0] * xv[r][i][0] + xv[r][i][1] * xv[r][i][1] + xv[r][i][2] * xv[r][i][2] + xv[r][i][3] * xv[r][i][3];
;                 ss = wave_sum(ss);
;                 const float rx = norm_out ? rsqrtf(ss * (1.0f / 1024.0f) + EPSN) : 1.0f;
; #pragma unroll
;                 for (int i = 0; i < 4; ++i) { u32x2 xw; xw.x = pkh2(xv[r][i][0], xv[r][i][1]); xw.y = pkh2(xv[r][i][2], xv[r][i][3]);
;                     __builtin_nontemporal_store(xw, (u32x2*)(X16 + (size_t)row * 1024 + (i * 64 + lane) * 4));
;                     u32x2 w; w.x = pk2(xv[r][i][0] * rx, xv[r][i][1] * rx); w.y = pk2(xv[r][i][2] * rx, xv[r][i][3] * rx);
;                     *(u32x2*)(out2 + (size_t)row * 1024 + (i * 64 + lane) * 4) = w; }
.LBB0_1312:
	s_or_b64 exec, exec, s[12:13]
	s_waitcnt vmcnt(4)
	v_cvt_f32_f16_sdwa v57, v52 dst_sel:DWORD dst_unused:UNUSED_PAD src0_sel:WORD_1
	v_cvt_f32_f16_e32 v56, v52
	ds_bpermute_b32 v52, v66, v12
	s_mov_b32 s0, 0x800000
	v_cvt_f32_f16_sdwa v59, v54 dst_sel:DWORD dst_unused:UNUSED_PAD src0_sel:WORD_1
	v_cvt_f32_f16_e32 v58, v54
	v_cvt_f32_f16_sdwa v61, v55 dst_sel:DWORD dst_unused:UNUSED_PAD src0_sel:WORD_1
	s_waitcnt lgkmcnt(0)
	v_add_f32_e32 v12, v12, v52
	ds_bpermute_b32 v52, v67, v12
	v_cvt_f32_f16_e32 v60, v55
	v_cvt_f32_f16_sdwa v75, v48 dst_sel:DWORD dst_unused:UNUSED_PAD src0_sel:WORD_1
	v_cvt_f32_f16_e32 v74, v48
	v_cvt_f32_f16_sdwa v77, v49 dst_sel:DWORD dst_unused:UNUSED_PAD src0_sel:WORD_1
	s_waitcnt lgkmcnt(0)
	v_add_f32_e32 v12, v12, v52
	ds_bpermute_b32 v52, v68, v12
	v_cvt_f32_f16_e32 v76, v49
	v_cvt_f32_f16_sdwa v63, v50 dst_sel:DWORD dst_unused:UNUSED_PAD src0_sel:WORD_1
	v_cvt_f32_f16_e32 v62, v50
	v_cvt_f32_f16_sdwa v49, v51 dst_sel:DWORD dst_unused:UNUSED_PAD src0_sel:WORD_1
	s_waitcnt lgkmcnt(0)
	v_add_f32_e32 v12, v12, v52
	ds_bpermute_b32 v52, v69, v12
	v_cvt_f32_f16_e32 v48, v51
	v_cvt_f32_f16_sdwa v51, v53 dst_sel:DWORD dst_unused:UNUSED_PAD src0_sel:WORD_1
	v_cvt_f32_f16_e32 v50, v53
	s_waitcnt vmcnt(3)
	v_lshlrev_b32_e32 v78, 16, v46
	s_waitcnt lgkmcnt(0)
	v_add_f32_e32 v12, v12, v52
	ds_bpermute_b32 v52, v70, v12
	v_and_b32_e32 v79, 0xffff0000, v46
	v_lshlrev_b32_e32 v46, 16, v47
	v_and_b32_e32 v47, 0xffff0000, v47
	v_lshl_add_u64 v[42:43], v[10:11], 0, v[42:43]
	s_waitcnt lgkmcnt(0)
	v_add_f32_e32 v12, v12, v52
	ds_bpermute_b32 v52, v71, v12
	s_waitcnt lgkmcnt(0)
	v_add_f32_e32 v12, v12, v52
	v_fmamk_f32 v12, v12, 0x3a800000, v168
	v_cmp_gt_f32_e64 s[40:41], s0, v12
	v_mul_f32_e32 v52, 0x4b800000, v12
	s_nop 0
	v_cndmask_b32_e64 v12, v12, v52, s[40:41]
	v_rsq_f32_e32 v12, v12
	s_nop 0
	v_mul_f32_e32 v52, 0x45800000, v12
	v_cndmask_b32_e64 v12, v12, v52, s[40:41]
	global_load_dwordx4 v[52:55], v[4:5], off
	v_pk_mul_f32 v[78:79], v[12:13], v[78:79] op_sel_hi:[0,1]
	v_pk_mul_f32 v[46:47], v[12:13], v[46:47] op_sel_hi:[0,1]
	s_waitcnt vmcnt(0)
	v_pk_fma_f32 v[58:59], v[52:53], v[78:79], v[58:59]
	v_pk_fma_f32 v[60:61], v[54:55], v[46:47], v[60:61]
	s_nop 1
	v_mov_b32_e32 v52, v244
	v_mov_b32_e32 v53, v245
	v_mov_b32_e32 v54, v246
	v_mov_b32_e32 v55, v247
	v_lshlrev_b32_e32 v46, 16, v2
	v_and_b32_e32 v47, 0xffff0000, v2
	v_lshlrev_b32_e32 v2, 16, v3
	v_and_b32_e32 v3, 0xffff0000, v3
	v_pk_mul_f32 v[46:47], v[12:13], v[46:47] op_sel_hi:[0,1]
	v_pk_mul_f32 v[2:3], v[12:13], v[2:3] op_sel_hi:[0,1]
	v_pk_fma_f32 v[52:53], v[52:53], v[46:47], v[74:75]
	v_pk_fma_f32 v[54:55], v[54:55], v[2:3], v[76:77]
	s_nop 1
	v_mov_b32_e32 v74, v248
	v_mov_b32_e32 v75, v249
	v_mov_b32_e32 v76, v250
	v_mov_b32_e32 v77, v251
	v_lshlrev_b32_e32 v2, 16, v0
	v_and_b32_e32 v3, 0xffff0000, v0
	v_lshlrev_b32_e32 v0, 16, v1
	v_and_b32_e32 v1, 0xffff0000, v1
	v_pk_mul_f32 v[2:3], v[12:13], v[2:3] op_sel_hi:[0,1]
	v_pk_mul_f32 v[0:1], v[12:13], v[0:1] op_sel_hi:[0,1]
	v_pk_fma_f32 v[46:47], v[74:75], v[2:3], v[62:63]
	v_pk_fma_f32 v[48:49], v[76:77], v[0:1], v[48:49]
	s_nop 1
	v_mov_b32_e32 v0, v252
	v_mov_b32_e32 v1, v253
	v_mov_b32_e32 v2, v254
	v_mov_b32_e32 v3, v255
	v_lshlrev_b32_e32 v62, 16, v44
	v_and_b32_e32 v63, 0xffff0000, v44
	v_lshlrev_b32_e32 v44, 16, v45
	v_and_b32_e32 v45, 0xffff0000, v45
	v_pk_mul_f32 v[44:45], v[12:13], v[44:45] op_sel_hi:[0,1]
	v_pk_mul_f32 v[62:63], v[12:13], v[62:63] op_sel_hi:[0,1]
	v_pk_fma_f32 v[2:3], v[2:3], v[44:45], v[50:51]
	v_mov_b32_e32 v50, v59
	v_mov_b32_e32 v51, v53
	v_mov_b32_e32 v44, v58
	v_mov_b32_e32 v45, v52
	v_pk_mul_f32 v[50:51], v[50:51], v[50:51]
	v_pk_fma_f32 v[0:1], v[0:1], v[62:63], v[56:57]
	v_pk_fma_f32 v[44:45], v[44:45], v[44:45], v[50:51]
	v_mov_b32_e32 v50, v60
	v_mov_b32_e32 v51, v54
	v_pk_fma_f32 v[44:45], v[50:51], v[50:51], v[44:45]
	v_mov_b32_e32 v50, v61
	v_mov_b32_e32 v51, v55
	v_mov_b32_e32 v56, v1
	v_mov_b32_e32 v57, v47
	v_pk_fma_f32 v[44:45], v[50:51], v[50:51], v[44:45]
	v_mov_b32_e32 v50, v0
	v_mov_b32_e32 v51, v46
	v_pk_mul_f32 v[56:57], v[56:57], v[56:57]
	v_add_f32_e32 v12, v44, v45
	v_pk_fma_f32 v[50:51], v[50:51], v[50:51], v[56:57]
	v_mov_b32_e32 v56, v2
	v_mov_b32_e32 v57, v48
	v_pk_fma_f32 v[50:51], v[56:57], v[56:57], v[50:51]
	v_mov_b32_e32 v56, v3
	v_mov_b32_e32 v57, v49
	v_pk_fma_f32 v[50:51], v[56:57], v[56:57], v[50:51]
	v_cvt_pk_f16_f32 v45, v60, v61
	v_add_f32_e32 v12, v51, v12
	v_add_f32_e32 v12, v50, v12
	ds_bpermute_b32 v44, v66, v12
	s_waitcnt lgkmcnt(0)
	v_add_f32_e32 v12, v12, v44
	ds_bpermute_b32 v44, v67, v12
	s_waitcnt lgkmcnt(0)
	v_add_f32_e32 v12, v12, v44
	ds_bpermute_b32 v44, v68, v12
	s_waitcnt lgkmcnt(0)
	v_add_f32_e32 v12, v12, v44
	ds_bpermute_b32 v44, v69, v12
	s_waitcnt lgkmcnt(0)
	v_add_f32_e32 v12, v12, v44
	ds_bpermute_b32 v44, v70, v12
	s_waitcnt lgkmcnt(0)
	v_add_f32_e32 v12, v12, v44
	ds_bpermute_b32 v44, v71, v12
	s_waitcnt lgkmcnt(0)
	v_add_f32_e32 v12, v12, v44
	v_fmamk_f32 v12, v12, 0x3a800000, v168
	v_cmp_gt_f32_e64 s[40:41], s0, v12
	v_mul_f32_e32 v44, 0x4b800000, v12
	s_nop 0
	v_cndmask_b32_e64 v12, v12, v44, s[40:41]
	v_rsq_f32_e32 v12, v12
	s_nop 0
	v_mul_f32_e32 v44, 0x45800000, v12
	v_cndmask_b32_e64 v12, v12, v44, s[40:41]
	v_cvt_pk_f16_f32 v44, v58, v59
	global_store_dwordx2 v[40:41], v[44:45], off nt
	v_pk_mul_f32 v[44:45], v[58:59], v[12:13] op_sel_hi:[1,0]
	v_pk_mul_f32 v[50:51], v[60:61], v[12:13] op_sel_hi:[1,0]
	v_cvt_pk_bf16_f32 v44, v44, v45
	v_cvt_pk_bf16_f32 v45, v50, v51
	global_store_dwordx2 v[42:43], v[44:45], off
	v_cvt_pk_f16_f32 v44, v52, v53
	v_cvt_pk_f16_f32 v45, v54, v55
	global_store_dwordx2 v[40:41], v[44:45], off offset:512 nt
	v_pk_mul_f32 v[44:45], v[52:53], v[12:13] op_sel_hi:[1,0]
	v_pk_mul_f32 v[50:51], v[54:55], v[12:13] op_sel_hi:[1,0]
	v_cvt_pk_bf16_f32 v44, v44, v45
	v_cvt_pk_bf16_f32 v45, v50, v51
	global_store_dwordx2 v[42:43], v[44:45], off offset:512
	v_cvt_pk_f16_f32 v44, v46, v47
	v_cvt_pk_f16_f32 v45, v48, v49
	global_store_dwordx2 v[40:41], v[44:45], off offset:1024 nt
	v_pk_mul_f32 v[44:45], v[46:47], v[12:13] op_sel_hi:[1,0]
	v_pk_mul_f32 v[46:47], v[48:49], v[12:13] op_sel_hi:[1,0]
	v_cvt_pk_bf16_f32 v44, v44, v45
	v_cvt_pk_bf16_f32 v45, v46, v47
	global_store_dwordx2 v[42:43], v[44:45], off offset:1024
	v_cvt_pk_f16_f32 v44, v0, v1
	v_cvt_pk_f16_f32 v45, v2, v3
	v_pk_mul_f32 v[0:1], v[0:1], v[12:13] op_sel_hi:[1,0]
	v_pk_mul_f32 v[2:3], v[2:3], v[12:13] op_sel_hi:[1,0]
	v_cvt_pk_bf16_f32 v0, v0, v1
	v_cvt_pk_bf16_f32 v1, v2, v3
	global_store_dwordx2 v[40:41], v[44:45], off offset:1536 nt
	global_store_dwordx2 v[42:43], v[0:1], off offset:1536
	s_and_saveexec_b64 s[12:13], s[38:39]
	s_cbranch_execz .LBB0_1305
; DI unsigned pk2(float a, float b) { f32x2 v = {a, b}; return __builtin_bit_cast(unsigned, __builtin_convertvector(v, bf2_t)); }
; DI float blo(unsigned w) { return __uint_as_float(w << 16); }
; DI float bhi(unsigned w) { return __uint_as_float(w & 0xffff0000u); }
; DI float wave_sum(float v) { for (int o = 32; o >= 1; o >>= 1) v += __shfl_xor(v, o); return v; }
; DI unsigned pkh2(float a, float b) { f32x2 v = {a, b}; return __builtin_bit_cast(unsigned, __builtin_convertvector(v, h2_t)); }
;     ...
;         for (int r = 0; r < RU; ++r) { const int rrow = row0 + r * nw; const int row = rev ? MTOK - 1 - rrow : rrow; if (rrow < MTOK) {
;             if (mode != 0) { const float rs = rsqrtf(wave_sum(sq[r]) * (1.0f / 1024.0f) + EPSN);
; #pragma unroll
;                 for (int i = 0; i < 4; ++i) { const f32x4 g4 = *(const f32x4*)(gain + (i * 64 + lane) * 4);
;                     xv[r][i][0] += blo(tw[r][i].x) * rs * g4[0]; xv[r][i][1] += bhi(tw[r][i].x) * rs * g4[1]; xv[r][i][2] += blo(tw[r][i].y) * rs * g4[2]; xv[r][i][3] += bhi(tw[r][i].y) * rs * g4[3]; } }
;             if (fin) {
; #pragma unroll
;                 for (int i = 0; i < 4; ++i) *(f32x4*)(P.out + (size_t)row * 1024 + (i * 64 + lane) * 4) = xv[r][i];
;             } else {
;                 float ss = 0.f;
; #pragma unroll
;                 for (int i = 0; i < 4; ++i) ss += xv[r][i][0] * xv[r][i][0] + xv[r][i][1] * xv[r][i][1] + xv[r][i][2] * xv[r][i][2] + xv[r][i][3] * xv[r][i][3];
;                 ss = wave_sum(ss);
;                 const float rx = norm_out ? rsqrtf(ss * (1.0f / 1024.0f) + EPSN) : 1.0f;
; #pragma unroll
;                 for (int i = 0; i < 4; ++i) { u32x2 xw; xw.x = pkh2(xv[r][i][0], xv[r][i][1]); xw.y = pkh2(xv[r][i][2], xv[r][i][3]);
;                     __builtin_nontemporal_store(xw, (u32x2*)(X16 + (size_t)row * 1024 + (i * 64 + lane) * 4));
;                     u32x2 w; w.x = pk2(xv[r][i][0] * rx, xv[r][i][1] * rx); w.y = pk2(xv[r][i][2] * rx, xv[r][i][3] * rx);
;                     *(u32x2*)(out2 + (size_t)row * 1024 + (i * 64 + lane) * 4) = w; }
	s_nop 1
	v_mov_b32_e32 v40, v240
	v_mov_b32_e32 v41, v241
	v_mov_b32_e32 v42, v242
	v_mov_b32_e32 v43, v243
	ds_bpermute_b32 v0, v66, v13
	v_lshlrev_b32_e32 v2, 16, v14
	v_and_b32_e32 v3, 0xffff0000, v14
	v_lshlrev_b64 v[38:39], 11, v[38:39]
	s_waitcnt lgkmcnt(0)
	v_add_f32_e32 v0, v13, v0
	ds_bpermute_b32 v1, v67, v0
	s_waitcnt lgkmcnt(0)
	v_add_f32_e32 v0, v0, v1
	ds_bpermute_b32 v1, v68, v0
	s_waitcnt lgkmcnt(0)
	v_add_f32_e32 v0, v0, v1
	ds_bpermute_b32 v1, v69, v0
	s_waitcnt lgkmcnt(0)
	v_add_f32_e32 v0, v0, v1
	ds_bpermute_b32 v1, v70, v0
	s_waitcnt lgkmcnt(0)
	v_add_f32_e32 v0, v0, v1
	ds_bpermute_b32 v1, v71, v0
	s_waitcnt lgkmcnt(0)
	v_add_f32_e32 v0, v0, v1
	v_fmamk_f32 v0, v0, 0x3a800000, v168
	v_cmp_gt_f32_e64 s[38:39], s0, v0
	v_mul_f32_e32 v1, 0x4b800000, v0
	s_nop 0
	v_cndmask_b32_e64 v0, v0, v1, s[38:39]
	v_rsq_f32_e32 v0, v0
	s_nop 0
	v_mul_f32_e32 v1, 0x45800000, v0
	v_cndmask_b32_e64 v0, v0, v1, s[38:39]
	v_pk_mul_f32 v[2:3], v[0:1], v[2:3] op_sel_hi:[0,1]
	v_pk_fma_f32 v[28:29], v[40:41], v[2:3], v[28:29]
	v_lshlrev_b32_e32 v2, 16, v15
	v_and_b32_e32 v3, 0xffff0000, v15
	v_pk_mul_f32 v[2:3], v[0:1], v[2:3] op_sel_hi:[0,1]
	v_pk_fma_f32 v[30:31], v[42:43], v[2:3], v[30:31]
	s_nop 1
	v_mov_b32_e32 v40, v244
	v_mov_b32_e32 v41, v245
	v_mov_b32_e32 v42, v246
	v_mov_b32_e32 v43, v247
	v_lshlrev_b32_e32 v2, 16, v16
	v_and_b32_e32 v3, 0xffff0000, v16
	v_pk_mul_f32 v[2:3], v[0:1], v[2:3] op_sel_hi:[0,1]
	v_pk_fma_f32 v[26:27], v[40:41], v[2:3], v[26:27]
	v_lshlrev_b32_e32 v2, 16, v17
	v_and_b32_e32 v3, 0xffff0000, v17
	v_pk_mul_f32 v[2:3], v[0:1], v[2:3] op_sel_hi:[0,1]
	v_pk_fma_f32 v[32:33], v[42:43], v[2:3], v[32:33]
	s_nop 1
	v_mov_b32_e32 v40, v248
	v_mov_b32_e32 v41, v249
	v_mov_b32_e32 v42, v250
	v_mov_b32_e32 v43, v251
	v_lshlrev_b32_e32 v2, 16, v18
	v_and_b32_e32 v3, 0xffff0000, v18
	v_pk_mul_f32 v[2:3], v[0:1], v[2:3] op_sel_hi:[0,1]
	v_pk_fma_f32 v[24:25], v[40:41], v[2:3], v[24:25]
	v_lshlrev_b32_e32 v2, 16, v19
	v_and_b32_e32 v3, 0xffff0000, v19
	v_pk_mul_f32 v[2:3], v[0:1], v[2:3] op_sel_hi:[0,1]
	v_pk_fma_f32 v[34:35], v[42:43], v[2:3], v[34:35]
	s_nop 1
	v_mov_b32_e32 v40, v252
	v_mov_b32_e32 v41, v253
	v_mov_b32_e32 v42, v254
	v_mov_b32_e32 v43, v255
	v_lshlrev_b32_e32 v2, 16, v20
	v_and_b32_e32 v3, 0xffff0000, v20
	v_pk_mul_f32 v[2:3], v[0:1], v[2:3] op_sel_hi:[0,1]
	v_pk_fma_f32 v[22:23], v[40:41], v[2:3], v[22:23]
	v_lshlrev_b32_e32 v2, 16, v21
	v_and_b32_e32 v3, 0xffff0000, v21
	v_pk_mul_f32 v[0:1], v[0:1], v[2:3] op_sel_hi:[0,1]
	v_mov_b32_e32 v2, v29
	v_mov_b32_e32 v3, v27
	v_pk_fma_f32 v[36:37], v[42:43], v[0:1], v[36:37]
	v_mov_b32_e32 v0, v28
	v_mov_b32_e32 v1, v26
	v_pk_mul_f32 v[2:3], v[2:3], v[2:3]
	v_mov_b32_e32 v40, v23
	v_pk_fma_f32 v[0:1], v[0:1], v[0:1], v[2:3]
	v_mov_b32_e32 v2, v30
	v_mov_b32_e32 v3, v32
	v_pk_fma_f32 v[0:1], v[2:3], v[2:3], v[0:1]
	v_mov_b32_e32 v2, v31
	v_mov_b32_e32 v3, v33
	v_mov_b32_e32 v41, v25
	v_pk_fma_f32 v[0:1], v[2:3], v[2:3], v[0:1]
	v_mov_b32_e32 v2, v22
	v_mov_b32_e32 v3, v24
	v_pk_mul_f32 v[40:41], v[40:41], v[40:41]
	v_add_f32_e32 v0, v0, v1
	v_pk_fma_f32 v[2:3], v[2:3], v[2:3], v[40:41]
	v_mov_b32_e32 v40, v36
	v_mov_b32_e32 v41, v34
	v_pk_fma_f32 v[2:3], v[40:41], v[40:41], v[2:3]
	v_mov_b32_e32 v40, v37
	v_mov_b32_e32 v41, v35
	v_pk_fma_f32 v[2:3], v[40:41], v[40:41], v[2:3]
	v_lshl_add_u64 v[40:41], v[6:7], 0, v[38:39]
	v_add_f32_e32 v0, v3, v0
	v_add_f32_e32 v0, v2, v0
	ds_bpermute_b32 v1, v66, v0
	v_cvt_pk_f16_f32 v2, v28, v29
	v_cvt_pk_f16_f32 v3, v30, v31
	global_store_dwordx2 v[40:41], v[2:3], off nt
	v_lshl_add_u64 v[38:39], v[10:11], 0, v[38:39]
	s_waitcnt lgkmcnt(0)
	v_add_f32_e32 v0, v0, v1
	ds_bpermute_b32 v1, v67, v0
	s_waitcnt lgkmcnt(0)
	v_add_f32_e32 v0, v0, v1
	ds_bpermute_b32 v1, v68, v0
	s_waitcnt lgkmcnt(0)
	v_add_f32_e32 v0, v0, v1
	ds_bpermute_b32 v1, v69, v0
	s_waitcnt lgkmcnt(0)
	v_add_f32_e32 v0, v0, v1
	ds_bpermute_b32 v1, v70, v0
	s_waitcnt lgkmcnt(0)
	v_add_f32_e32 v0, v0, v1
	ds_bpermute_b32 v1, v71, v0
	s_waitcnt lgkmcnt(0)
	v_add_f32_e32 v0, v0, v1
	v_fmamk_f32 v0, v0, 0x3a800000, v168
	v_cmp_gt_f32_e64 s[38:39], s0, v0
	v_mul_f32_e32 v1, 0x4b800000, v0
	s_nop 0
	v_cndmask_b32_e64 v0, v0, v1, s[38:39]
	v_rsq_f32_e32 v0, v0
	s_nop 0
	v_mul_f32_e32 v1, 0x45800000, v0
	v_cndmask_b32_e64 v0, v0, v1, s[38:39]
	v_pk_mul_f32 v[2:3], v[28:29], v[0:1] op_sel_hi:[1,0]
	v_pk_mul_f32 v[42:43], v[30:31], v[0:1] op_sel_hi:[1,0]
	v_cvt_pk_bf16_f32 v2, v2, v3
	v_cvt_pk_bf16_f32 v3, v42, v43
	global_store_dwordx2 v[38:39], v[2:3], off
	v_cvt_pk_f16_f32 v2, v26, v27
	v_cvt_pk_f16_f32 v3, v32, v33
	global_store_dwordx2 v[40:41], v[2:3], off offset:512 nt
	v_pk_mul_f32 v[2:3], v[26:27], v[0:1] op_sel_hi:[1,0]
	v_pk_mul_f32 v[42:43], v[32:33], v[0:1] op_sel_hi:[1,0]
	v_cvt_pk_bf16_f32 v2, v2, v3
	v_cvt_pk_bf16_f32 v3, v42, v43
	global_store_dwordx2 v[38:39], v[2:3], off offset:512
	v_cvt_pk_f16_f32 v2, v24, v25
	v_cvt_pk_f16_f32 v3, v34, v35
	global_store_dwordx2 v[40:41], v[2:3], off offset:1024 nt
	v_pk_mul_f32 v[2:3], v[24:25], v[0:1] op_sel_hi:[1,0]
	v_pk_mul_f32 v[42:43], v[34:35], v[0:1] op_sel_hi:[1,0]
	v_cvt_pk_bf16_f32 v2, v2, v3
	v_cvt_pk_bf16_f32 v3, v42, v43
	global_store_dwordx2 v[38:39], v[2:3], off offset:1024
	v_cvt_pk_f16_f32 v2, v22, v23
	v_cvt_pk_f16_f32 v3, v36, v37
	global_store_dwordx2 v[40:41], v[2:3], off offset:1536 nt
	v_pk_mul_f32 v[2:3], v[22:23], v[0:1] op_sel_hi:[1,0]
	v_pk_mul_f32 v[0:1], v[36:37], v[0:1] op_sel_hi:[1,0]
	v_cvt_pk_bf16_f32 v2, v2, v3
	v_cvt_pk_bf16_f32 v3, v0, v1
	global_store_dwordx2 v[38:39], v[2:3], off offset:1536
	s_branch .LBB0_1305

; DI int opaque_tid() { int t = threadIdx.x; asm volatile("" : "+v"(t)); return t; }
; DI int opaque_s(int t) { asm volatile("" : "+s"(t)); return t; }
; DI float wave_sum(float v) { for (int o = 32; o >= 1; o >>= 1) v += __shfl_xor(v, o); return v; }
; DI f32x2 unh2(unsigned w) { return __builtin_convertvector(__builtin_bit_cast(h2_t, w), f32x2); }
;     const int tid_ = opaque_tid(); const int lane = tid_ & 63, gw = opaque_s(blockIdx.x) * 8 + (tid_ >> 6), nw = opaque_s(gridDim.x) * 8;
;     const float* ssq_t = (const float*)(P.ws + WS_SSQT);
;     bf16_t* pb = (bf16_t*)(P.ws + A_PB);
;     unsigned short* X16 = (unsigned short*)(P.ws + A_H);
;     constexpr int RU = 2;
;     for (int row0 = gw; row0 < MTOK; row0 += RU * nw) {
;         f32x4 xv[RU][4]; u32x2 tw[RU][4]; float sq[RU]; f32x4 pv[RU];
; #pragma unroll
;         for (int r = 0; r < RU; ++r) { const int rrow = row0 + r * nw; const int row = rev ? MTOK - 1 - rrow : rrow; if (rrow < MTOK) {
;             if (mode == 0) { const float* xs = row < NPROMPT ? P.in[0] + (size_t)row * 1024 : P.in[1] + (size_t)(row - NPROMPT) * 1024;
; #pragma unroll
;                 for (int i = 0; i < 4; ++i) xv[r][i] = *(const f32x4*)(xs + (i * 64 + lane) * 4);
;             } else {
; #pragma unroll
;                 for (int i = 0; i < 4; ++i) { const u32x2 xw = __builtin_nontemporal_load((const u32x2*)(X16 + (size_t)row * 1024 + (i * 64 + lane) * 4)); const f32x2 a = unh2(xw.x), c = unh2(xw.y); xv[r][i] = (f32x4){a.x, a.y, c.x, c.y}; }
;                 sq[r] = lane < 16 ? ssq_t[row * 16 + lane] : 0.f;
; #pragma unroll
;                 for (int i = 0; i < 4; ++i) tw[r][i] = __builtin_nontemporal_load((const u32x2*)(T + (size_t)row * 1024 + (i * 64 + lane) * 4)); }
;             if (mode == 2) { const float* pp = row < NPROMPT ? P.in[2] + ((size_t)layer * NPROMPT + row) * 256 : P.in[3] + ((size_t)layer * (MTOK - NPROMPT) + (row - NPROMPT)) * 256;
;                 pv[r] = *(const f32x4*)(pp + lane * 4); } } }
; #pragma unroll
;         for (int r = 0; r < RU; ++r) { const int rrow = row0 + r * nw; const int row = rev ? MTOK - 1 - rrow : rrow; if (rrow < MTOK) {
;             if (mode != 0) { const float rs = rsqrtf(wave_sum(sq[r]) * (1.0f / 1024.0f) + EPSN);
; #pragma unroll
;                 for (int i = 0; i < 4; ++i) { const f32x4 g4 = *(const f32x4*)(gain + (i * 64 + lane) * 4);
.LBB0_1522:
	s_or_b64 exec, exec, s[2:3]
	v_mov_b32_e32 v1, v164
	v_readlane_b32 s0, v238, 0
	s_waitcnt lgkmcnt(0)
	s_barrier
	s_lshl_b32 s4, s0, 3
	v_ashrrev_i32_e32 v0, 6, v1
	v_add_u32_e32 v13, s4, v0
	s_mov_b32 s5, s68
	v_cmp_gt_i32_e32 vcc, s56, v13
	s_and_saveexec_b64 s[2:3], vcc
	s_cbranch_execz .LBB0_1533
	v_readlane_b32 s36, v238, 1
	s_lshl_b32 s0, s5, 3
	s_lshl_b64 s[10:11], s[8:9], 2
	v_readlane_b32 s40, v238, 5
	v_and_b32_e32 v74, 63, v1
	v_readlane_b32 s38, v238, 3
	v_readlane_b32 s39, v238, 4
	v_readlane_b32 s41, v238, 6
	s_add_u32 s10, s40, s10
	v_add_u32_e32 v1, 64, v148
	s_addc_u32 s11, s41, s11
	v_readlane_b32 s14, v236, 41
	v_lshlrev_b32_e32 v2, 4, v74
	v_mov_b32_e32 v3, v167
	v_cmp_lt_i32_e64 s[38:39], v147, v1
	v_readlane_b32 s15, v236, 42
	v_readlane_b32 s16, v237, 53
	v_lshl_add_u64 v[16:17], s[10:11], 0, v[2:3]
	global_load_dwordx4 v[240:243], v[16:17], off
	global_load_dwordx4 v[244:247], v[16:17], off offset:1024
	global_load_dwordx4 v[248:251], v[16:17], off offset:2048
	global_load_dwordx4 v[252:255], v[16:17], off offset:3072
	v_cndmask_b32_e64 v2, v184, v147, s[38:39]
	v_cmp_lt_i32_e64 s[38:39], v146, v1
	s_mov_b32 s15, s9
	v_lshlrev_b32_e32 v166, 3, v74
	v_readlane_b32 s17, v237, 54
	v_lshlrev_b32_e32 v75, 2, v2
	v_cndmask_b32_e64 v2, v184, v146, s[38:39]
	v_cmp_lt_i32_e64 s[38:39], v145, v1
	s_lshl_b64 s[12:13], s[14:15], 24
	s_lshl_b64 s[14:15], s[14:15], 25
	v_lshl_add_u64 v[14:15], s[16:17], 0, v[166:167]
	s_lshl_b32 s16, s5, 4
	v_lshlrev_b32_e32 v76, 2, v2
	v_cndmask_b32_e64 v2, v184, v145, s[38:39]
	v_cmp_lt_i32_e64 s[38:39], v144, v1
	s_add_u32 s17, s22, s12
	v_lshlrev_b32_e32 v77, 2, v2
	v_cndmask_b32_e64 v2, v184, v144, s[38:39]
	v_cmp_lt_i32_e64 s[38:39], v143, v1
	v_readlane_b32 s44, v238, 9
	v_readlane_b32 s45, v238, 10
	v_readlane_b32 s46, v238, 11
	v_readlane_b32 s47, v238, 12
	v_readlane_b32 s48, v238, 13
	v_readlane_b32 s49, v238, 14
	s_addc_u32 s18, s23, s13
	v_lshlrev_b32_e32 v78, 2, v2
	v_cndmask_b32_e64 v2, v184, v143, s[38:39]
	v_cmp_lt_i32_e64 s[38:39], v142, v1
	v_readlane_b32 s10, v238, 19
	v_add_u32_e32 v0, s4, v0
	v_readlane_b32 s42, v238, 7
	v_readlane_b32 s46, v238, 30
	v_readlane_b32 s44, v236, 23
	s_add_u32 s19, s20, s14
	v_cndmask_b32_e64 v1, v184, v142, s[38:39]
	v_readlane_b32 s11, v238, 20
	v_lshl_add_u64 v[20:21], s[48:49], 0, v[166:167]
	v_readlane_b32 s48, v236, 25
	v_sub_u32_e32 v81, 0xbfff, v0
	v_mov_b32_e32 v0, 0
	v_readlane_b32 s47, v238, 31
	v_readlane_b32 s45, v236, 24
	v_readlane_b32 s42, v236, 20
	v_lshlrev_b32_e32 v12, 2, v74
	v_cmp_gt_u32_e32 vcc, 16, v74
	s_addc_u32 s33, s21, s15
	v_lshlrev_b32_e32 v79, 2, v2
	v_lshlrev_b32_e32 v80, 2, v1
	v_lshl_add_u64 v[18:19], s[10:11], 0, v[166:167]
	v_readlane_b32 s49, v236, 26
	s_sub_i32 s36, 0, s0
	s_mov_b64 s[10:11], 0
	v_mov_b64_e32 v[22:23], v[166:167]
	v_mov_b32_e32 v1, v0
	v_mov_b32_e32 v2, v0
	v_mov_b32_e32 v3, v0
	v_readlane_b32 s37, v238, 2
	v_readlane_b32 s43, v238, 8
	v_readlane_b32 s50, v238, 15
	v_readlane_b32 s51, v238, 16
	s_branch .LBB0_1525

; DI unsigned pk2(float a, float b) { f32x2 v = {a, b}; return __builtin_bit_cast(unsigned, __builtin_convertvector(v, bf2_t)); }
; DI float blo(unsigned w) { return __uint_as_float(w << 16); }
; DI float bhi(unsigned w) { return __uint_as_float(w & 0xffff0000u); }
; DI float wave_sum(float v) { for (int o = 32; o >= 1; o >>= 1) v += __shfl_xor(v, o); return v; }
; DI unsigned pkh2(float a, float b) { f32x2 v = {a, b}; return __builtin_bit_cast(unsigned, __builtin_convertvector(v, h2_t)); }
;     ...
;         for (int r = 0; r < RU; ++r) { const int rrow = row0 + r * nw; const int row = rev ? MTOK - 1 - rrow : rrow; if (rrow < MTOK) {
;             if (mode != 0) { const float rs = rsqrtf(wave_sum(sq[r]) * (1.0f / 1024.0f) + EPSN);
; #pragma unroll
;                 for (int i = 0; i < 4; ++i) { const f32x4 g4 = *(const f32x4*)(gain + (i * 64 + lane) * 4);
;                     xv[r][i][0] += blo(tw[r][i].x) * rs * g4[0]; xv[r][i][1] += bhi(tw[r][i].x) * rs * g4[1]; xv[r][i][2] += blo(tw[r][i].y) * rs * g4[2]; xv[r][i][3] += bhi(tw[r][i].y) * rs * g4[3]; } }
;             if (fin) {
; #pragma unroll
;                 for (int i = 0; i < 4; ++i) *(f32x4*)(P.out + (size_t)row * 1024 + (i * 64 + lane) * 4) = xv[r][i];
;             } else {
;                 float ss = 0.f;
; #pragma unroll
;                 for (int i = 0; i < 4; ++i) ss += xv[r][i][0] * xv[r][i][0] + xv[r][i][1] * xv[r][i][1] + xv[r][i][2] * xv[r][i][2] + xv[r][i][3] * xv[r][i][3];
;                 ss = wave_sum(ss);
;                 const float rx = norm_out ? rsqrtf(ss * (1.0f / 1024.0f) + EPSN) : 1.0f;
; #pragma unroll
;                 for (int i = 0; i < 4; ++i) { u32x2 xw; xw.x = pkh2(xv[r][i][0], xv[r][i][1]); xw.y = pkh2(xv[r][i][2], xv[r][i][3]);
;                     __builtin_nontemporal_store(xw, (u32x2*)(X16 + (size_t)row * 1024 + (i * 64 + lane) * 4));
;                     u32x2 w; w.x = pk2(xv[r][i][0] * rx, xv[r][i][1] * rx); w.y = pk2(xv[r][i][2] * rx, xv[r][i][3] * rx);
;                     *(u32x2*)(out2 + (size_t)row * 1024 + (i * 64 + lane) * 4) = w; }
;                 if (mode == 2) { u32x2 w; w.x = pk2(pv[r][0], pv[r][1]); w.y = pk2(pv[r][2], pv[r][3]); *(u32x2*)(pb + (size_t)row * 256 + lane * 4) = w; } } } }
.LBB0_1531:
	s_or_b64 exec, exec, s[12:13]
	s_waitcnt vmcnt(7)
	v_cvt_f32_f16_sdwa v85, v60 dst_sel:DWORD dst_unused:UNUSED_PAD src0_sel:WORD_1
	v_cvt_f32_f16_e32 v84, v60
	v_cvt_f32_f16_sdwa v87, v61 dst_sel:DWORD dst_unused:UNUSED_PAD src0_sel:WORD_1
	v_cvt_f32_f16_e32 v86, v61
	s_waitcnt vmcnt(5)
	v_cvt_f32_f16_sdwa v61, v64 dst_sel:DWORD dst_unused:UNUSED_PAD src0_sel:WORD_1
	v_cvt_f32_f16_e32 v60, v64
	ds_bpermute_b32 v64, v75, v22
	s_mov_b32 s4, 0x800000
	v_cvt_f32_f16_sdwa v69, v66 dst_sel:DWORD dst_unused:UNUSED_PAD src0_sel:WORD_1
	v_cvt_f32_f16_e32 v68, v66
	v_cvt_f32_f16_sdwa v83, v67 dst_sel:DWORD dst_unused:UNUSED_PAD src0_sel:WORD_1
	s_waitcnt lgkmcnt(0)
	v_add_f32_e32 v22, v22, v64
	ds_bpermute_b32 v64, v76, v22
	v_cvt_f32_f16_e32 v82, v67
	v_cvt_f32_f16_sdwa v71, v58 dst_sel:DWORD dst_unused:UNUSED_PAD src0_sel:WORD_1
	v_cvt_f32_f16_e32 v70, v58
	v_cvt_f32_f16_sdwa v73, v59 dst_sel:DWORD dst_unused:UNUSED_PAD src0_sel:WORD_1
	s_waitcnt lgkmcnt(0)
	v_add_f32_e32 v22, v22, v64
	ds_bpermute_b32 v64, v77, v22
	v_cvt_f32_f16_e32 v72, v59
	v_cvt_f32_f16_sdwa v59, v65 dst_sel:DWORD dst_unused:UNUSED_PAD src0_sel:WORD_1
	v_cvt_f32_f16_e32 v58, v65
	s_waitcnt vmcnt(4)
	v_lshlrev_b32_e32 v88, 16, v62
	s_waitcnt lgkmcnt(0)
	v_add_f32_e32 v22, v22, v64
	ds_bpermute_b32 v64, v78, v22
	v_and_b32_e32 v89, 0xffff0000, v62
	v_lshlrev_b32_e32 v62, 16, v63
	v_and_b32_e32 v63, 0xffff0000, v63
	s_waitcnt vmcnt(0)
	v_cvt_pk_bf16_f32 v4, v4, v5
	s_waitcnt lgkmcnt(0)
	v_add_f32_e32 v22, v22, v64
	ds_bpermute_b32 v64, v79, v22
	v_cvt_pk_bf16_f32 v5, v6, v7
	v_lshlrev_b64 v[6:7], 9, v[50:51]
	v_lshl_add_u64 v[6:7], v[14:15], 0, v[6:7]
	s_waitcnt lgkmcnt(0)
	v_add_f32_e32 v22, v22, v64
	ds_bpermute_b32 v64, v80, v22
	s_waitcnt lgkmcnt(0)
	v_add_f32_e32 v22, v22, v64
	v_fmamk_f32 v22, v22, 0x3a800000, v168
	v_cmp_gt_f32_e64 s[40:41], s4, v22
	v_mul_f32_e32 v64, 0x4b800000, v22
	s_nop 0
	v_cndmask_b32_e64 v22, v22, v64, s[40:41]
	v_rsq_f32_e32 v22, v22
	s_nop 0
	v_mul_f32_e32 v64, 0x45800000, v22
	v_cndmask_b32_e64 v22, v22, v64, s[40:41]
	global_load_dwordx4 v[64:67], v[16:17], off
	v_pk_mul_f32 v[88:89], v[22:23], v[88:89] op_sel_hi:[0,1]
	v_pk_mul_f32 v[62:63], v[22:23], v[62:63] op_sel_hi:[0,1]
	s_waitcnt vmcnt(0)
	v_pk_fma_f32 v[64:65], v[64:65], v[88:89], v[68:69]
	v_pk_fma_f32 v[62:63], v[66:67], v[62:63], v[82:83]
	s_nop 1
	v_mov_b32_e32 v66, v244
	v_mov_b32_e32 v67, v245
	v_mov_b32_e32 v68, v246
	v_mov_b32_e32 v69, v247
	v_lshlrev_b32_e32 v82, 16, v10
	v_and_b32_e32 v83, 0xffff0000, v10
	v_pk_mul_f32 v[82:83], v[22:23], v[82:83] op_sel_hi:[0,1]
	v_lshlrev_b32_e32 v10, 16, v11
	v_and_b32_e32 v11, 0xffff0000, v11
	v_pk_mul_f32 v[10:11], v[22:23], v[10:11] op_sel_hi:[0,1]
	v_pk_fma_f32 v[66:67], v[66:67], v[82:83], v[84:85]
	s_nop 1
	v_mov_b32_e32 v82, v248
	v_mov_b32_e32 v83, v249
	v_mov_b32_e32 v84, v250
	v_mov_b32_e32 v85, v251
	v_pk_fma_f32 v[68:69], v[68:69], v[10:11], v[86:87]
	v_lshlrev_b32_e32 v10, 16, v8
	v_and_b32_e32 v11, 0xffff0000, v8
	v_lshlrev_b32_e32 v8, 16, v9
	v_and_b32_e32 v9, 0xffff0000, v9
	v_pk_mul_f32 v[10:11], v[22:23], v[10:11] op_sel_hi:[0,1]
	v_pk_mul_f32 v[8:9], v[22:23], v[8:9] op_sel_hi:[0,1]
	v_pk_fma_f32 v[70:71], v[82:83], v[10:11], v[70:71]
	v_pk_fma_f32 v[72:73], v[84:85], v[8:9], v[72:73]
	s_nop 1
	v_mov_b32_e32 v8, v252
	v_mov_b32_e32 v9, v253
	v_mov_b32_e32 v10, v254
	v_mov_b32_e32 v11, v255
	v_lshlrev_b32_e32 v82, 16, v56
	v_and_b32_e32 v83, 0xffff0000, v56
	v_lshlrev_b32_e32 v56, 16, v57
	v_and_b32_e32 v57, 0xffff0000, v57
	v_pk_mul_f32 v[56:57], v[22:23], v[56:57] op_sel_hi:[0,1]
	v_pk_mul_f32 v[82:83], v[22:23], v[82:83] op_sel_hi:[0,1]
	v_pk_fma_f32 v[10:11], v[10:11], v[56:57], v[58:59]
	v_cvt_pk_f16_f32 v56, v64, v65
	v_cvt_pk_f16_f32 v57, v62, v63
	global_store_dwordx2 v[52:53], v[56:57], off nt
	v_cvt_pk_bf16_f32 v56, v64, v65
	v_cvt_pk_bf16_f32 v57, v62, v63
	global_store_dwordx2 v[54:55], v[56:57], off
	v_cvt_pk_f16_f32 v56, v66, v67
	v_cvt_pk_f16_f32 v57, v68, v69
	global_store_dwordx2 v[52:53], v[56:57], off offset:512 nt
	v_cvt_pk_bf16_f32 v56, v66, v67
	v_cvt_pk_bf16_f32 v57, v68, v69
	global_store_dwordx2 v[54:55], v[56:57], off offset:512
	v_cvt_pk_f16_f32 v56, v70, v71
	v_cvt_pk_f16_f32 v57, v72, v73
	v_pk_fma_f32 v[8:9], v[8:9], v[82:83], v[60:61]
	global_store_dwordx2 v[52:53], v[56:57], off offset:1024 nt
	v_cvt_pk_bf16_f32 v56, v70, v71
	v_cvt_pk_bf16_f32 v57, v72, v73
	global_store_dwordx2 v[54:55], v[56:57], off offset:1024
	v_cvt_pk_f16_f32 v56, v8, v9
	v_cvt_pk_f16_f32 v57, v10, v11
	v_cvt_pk_bf16_f32 v8, v8, v9
	v_cvt_pk_bf16_f32 v9, v10, v11
	global_store_dwordx2 v[52:53], v[56:57], off offset:1536 nt
	global_store_dwordx2 v[54:55], v[8:9], off offset:1536
	global_store_dwordx2 v[6:7], v[4:5], off
	s_and_saveexec_b64 s[12:13], s[38:39]
	s_cbranch_execz .LBB0_1524
; DI unsigned pk2(float a, float b) { f32x2 v = {a, b}; return __builtin_bit_cast(unsigned, __builtin_convertvector(v, bf2_t)); }
; DI float blo(unsigned w) { return __uint_as_float(w << 16); }
; DI float bhi(unsigned w) { return __uint_as_float(w & 0xffff0000u); }
; DI float wave_sum(float v) { for (int o = 32; o >= 1; o >>= 1) v += __shfl_xor(v, o); return v; }
; DI unsigned pkh2(float a, float b) { f32x2 v = {a, b}; return __builtin_bit_cast(unsigned, __builtin_convertvector(v, h2_t)); }
;     ...
;         for (int r = 0; r < RU; ++r) { const int rrow = row0 + r * nw; const int row = rev ? MTOK - 1 - rrow : rrow; if (rrow < MTOK) {
;             if (mode != 0) { const float rs = rsqrtf(wave_sum(sq[r]) * (1.0f / 1024.0f) + EPSN);
; #pragma unroll
;                 for (int i = 0; i < 4; ++i) { const f32x4 g4 = *(const f32x4*)(gain + (i * 64 + lane) * 4);
;                     xv[r][i][0] += blo(tw[r][i].x) * rs * g4[0]; xv[r][i][1] += bhi(tw[r][i].x) * rs * g4[1]; xv[r][i][2] += blo(tw[r][i].y) * rs * g4[2]; xv[r][i][3] += bhi(tw[r][i].y) * rs * g4[3]; } }
;             if (fin) {
; #pragma unroll
;                 for (int i = 0; i < 4; ++i) *(f32x4*)(P.out + (size_t)row * 1024 + (i * 64 + lane) * 4) = xv[r][i];
;             } else {
;                 float ss = 0.f;
; #pragma unroll
;                 for (int i = 0; i < 4; ++i) ss += xv[r][i][0] * xv[r][i][0] + xv[r][i][1] * xv[r][i][1] + xv[r][i][2] * xv[r][i][2] + xv[r][i][3] * xv[r][i][3];
;                 ss = wave_sum(ss);
;                 const float rx = norm_out ? rsqrtf(ss * (1.0f / 1024.0f) + EPSN) : 1.0f;
; #pragma unroll
;                 for (int i = 0; i < 4; ++i) { u32x2 xw; xw.x = pkh2(xv[r][i][0], xv[r][i][1]); xw.y = pkh2(xv[r][i][2], xv[r][i][3]);
;                     __builtin_nontemporal_store(xw, (u32x2*)(X16 + (size_t)row * 1024 + (i * 64 + lane) * 4));
;                     u32x2 w; w.x = pk2(xv[r][i][0] * rx, xv[r][i][1] * rx); w.y = pk2(xv[r][i][2] * rx, xv[r][i][3] * rx);
;                     *(u32x2*)(out2 + (size_t)row * 1024 + (i * 64 + lane) * 4) = w; }
;                 if (mode == 2) { u32x2 w; w.x = pk2(pv[r][0], pv[r][1]); w.y = pk2(pv[r][2], pv[r][3]); *(u32x2*)(pb + (size_t)row * 256 + lane * 4) = w; } } } }
	s_nop 1
	v_mov_b32_e32 v6, v240
	v_mov_b32_e32 v7, v241
	v_mov_b32_e32 v8, v242
	v_mov_b32_e32 v9, v243
	ds_bpermute_b32 v4, v75, v23
	v_lshlrev_b32_e32 v10, 16, v24
	v_and_b32_e32 v11, 0xffff0000, v24
	s_waitcnt lgkmcnt(0)
	v_add_f32_e32 v4, v23, v4
	ds_bpermute_b32 v5, v76, v4
	s_waitcnt lgkmcnt(0)
	v_add_f32_e32 v4, v4, v5
	ds_bpermute_b32 v5, v77, v4
	s_waitcnt lgkmcnt(0)
	v_add_f32_e32 v4, v4, v5
	ds_bpermute_b32 v5, v78, v4
	s_waitcnt lgkmcnt(0)
	v_add_f32_e32 v4, v4, v5
	ds_bpermute_b32 v5, v79, v4
	s_waitcnt lgkmcnt(0)
	v_add_f32_e32 v4, v4, v5
	ds_bpermute_b32 v5, v80, v4
	s_waitcnt lgkmcnt(0)
	v_add_f32_e32 v4, v4, v5
	v_fmamk_f32 v4, v4, 0x3a800000, v168
	v_cmp_gt_f32_e64 s[38:39], s4, v4
	v_mul_f32_e32 v5, 0x4b800000, v4
	s_nop 0
	v_cndmask_b32_e64 v4, v4, v5, s[38:39]
	v_rsq_f32_e32 v4, v4
	s_nop 0
	v_mul_f32_e32 v5, 0x45800000, v4
	v_cndmask_b32_e64 v4, v4, v5, s[38:39]
	v_pk_mul_f32 v[10:11], v[4:5], v[10:11] op_sel_hi:[0,1]
	v_pk_fma_f32 v[38:39], v[6:7], v[10:11], v[38:39]
	v_lshlrev_b32_e32 v6, 16, v25
	v_and_b32_e32 v7, 0xffff0000, v25
	v_pk_mul_f32 v[6:7], v[4:5], v[6:7] op_sel_hi:[0,1]
	v_pk_fma_f32 v[40:41], v[8:9], v[6:7], v[40:41]
	s_nop 1
	v_mov_b32_e32 v6, v244
	v_mov_b32_e32 v7, v245
	v_mov_b32_e32 v8, v246
	v_mov_b32_e32 v9, v247
	v_lshlrev_b32_e32 v10, 16, v26
	v_and_b32_e32 v11, 0xffff0000, v26
	v_pk_mul_f32 v[10:11], v[4:5], v[10:11] op_sel_hi:[0,1]
	v_pk_fma_f32 v[36:37], v[6:7], v[10:11], v[36:37]
	v_lshlrev_b32_e32 v6, 16, v27
	v_and_b32_e32 v7, 0xffff0000, v27
	v_pk_mul_f32 v[6:7], v[4:5], v[6:7] op_sel_hi:[0,1]
	v_pk_fma_f32 v[42:43], v[8:9], v[6:7], v[42:43]
	s_nop 1
	v_mov_b32_e32 v6, v248
	v_mov_b32_e32 v7, v249
	v_mov_b32_e32 v8, v250
	v_mov_b32_e32 v9, v251
	v_lshlrev_b32_e32 v10, 16, v28
	v_and_b32_e32 v11, 0xffff0000, v28
	v_pk_mul_f32 v[10:11], v[4:5], v[10:11] op_sel_hi:[0,1]
	v_pk_fma_f32 v[34:35], v[6:7], v[10:11], v[34:35]
	v_lshlrev_b32_e32 v6, 16, v29
	v_and_b32_e32 v7, 0xffff0000, v29
	v_pk_mul_f32 v[6:7], v[4:5], v[6:7] op_sel_hi:[0,1]
	v_pk_fma_f32 v[44:45], v[8:9], v[6:7], v[44:45]
	s_nop 1
	v_mov_b32_e32 v6, v252
	v_mov_b32_e32 v7, v253
	v_mov_b32_e32 v8, v254
	v_mov_b32_e32 v9, v255
	v_lshlrev_b32_e32 v10, 16, v30
	v_and_b32_e32 v11, 0xffff0000, v30
	v_pk_mul_f32 v[10:11], v[4:5], v[10:11] op_sel_hi:[0,1]
	v_pk_fma_f32 v[32:33], v[6:7], v[10:11], v[32:33]
	v_lshlrev_b32_e32 v6, 16, v31
	v_and_b32_e32 v7, 0xffff0000, v31
	v_pk_mul_f32 v[4:5], v[4:5], v[6:7] op_sel_hi:[0,1]
	v_lshlrev_b64 v[6:7], 11, v[48:49]
	v_pk_fma_f32 v[46:47], v[8:9], v[4:5], v[46:47]
	v_cvt_pk_f16_f32 v4, v38, v39
	v_cvt_pk_f16_f32 v5, v40, v41
	v_lshl_add_u64 v[8:9], v[18:19], 0, v[6:7]
	global_store_dwordx2 v[8:9], v[4:5], off nt
	v_cvt_pk_bf16_f32 v4, v38, v39
	v_cvt_pk_bf16_f32 v5, v40, v41
	v_lshl_add_u64 v[6:7], v[20:21], 0, v[6:7]
	global_store_dwordx2 v[6:7], v[4:5], off
	v_cvt_pk_f16_f32 v4, v36, v37
	v_cvt_pk_f16_f32 v5, v42, v43
	global_store_dwordx2 v[8:9], v[4:5], off offset:512 nt
	v_cvt_pk_bf16_f32 v4, v36, v37
	v_cvt_pk_bf16_f32 v5, v42, v43
	global_store_dwordx2 v[6:7], v[4:5], off offset:512
	v_cvt_pk_f16_f32 v4, v34, v35
	v_cvt_pk_f16_f32 v5, v44, v45
	global_store_dwordx2 v[8:9], v[4:5], off offset:1024 nt
	v_cvt_pk_bf16_f32 v4, v34, v35
	v_cvt_pk_bf16_f32 v5, v44, v45
	global_store_dwordx2 v[6:7], v[4:5], off offset:1024
	v_cvt_pk_f16_f32 v4, v32, v33
	v_cvt_pk_f16_f32 v5, v46, v47
	global_store_dwordx2 v[8:9], v[4:5], off offset:1536 nt
	v_cvt_pk_bf16_f32 v4, v32, v33
	v_cvt_pk_bf16_f32 v5, v46, v47
	global_store_dwordx2 v[6:7], v[4:5], off offset:1536
	v_lshlrev_b64 v[6:7], 9, v[48:49]
	v_cvt_pk_bf16_f32 v4, v0, v1
	v_cvt_pk_bf16_f32 v5, v2, v3
	v_lshl_add_u64 v[6:7], v[14:15], 0, v[6:7]
	global_store_dwordx2 v[6:7], v[4:5], off
	s_branch .LBB0_1524

; DI int opaque_tid() { int t = threadIdx.x; asm volatile("" : "+v"(t)); return t; }
; DI int opaque_s(int t) { asm volatile("" : "+s"(t)); return t; }
; DI float wave_sum(float v) { for (int o = 32; o >= 1; o >>= 1) v += __shfl_xor(v, o); return v; }
; DI f32x2 unh2(unsigned w) { return __builtin_convertvector(__builtin_bit_cast(h2_t, w), f32x2); }
;     const int tid_ = opaque_tid(); const int lane = tid_ & 63, gw = opaque_s(blockIdx.x) * 8 + (tid_ >> 6), nw = opaque_s(gridDim.x) * 8;
;     const float* ssq_t = (const float*)(P.ws + WS_SSQT);
;     bf16_t* pb = (bf16_t*)(P.ws + A_PB);
;     unsigned short* X16 = (unsigned short*)(P.ws + A_H);
;     constexpr int RU = 2;
;     for (int row0 = gw; row0 < MTOK; row0 += RU * nw) {
;         f32x4 xv[RU][4]; u32x2 tw[RU][4]; float sq[RU]; f32x4 pv[RU];
; #pragma unroll
;         for (int r = 0; r < RU; ++r) { const int rrow = row0 + r * nw; const int row = rev ? MTOK - 1 - rrow : rrow; if (rrow < MTOK) {
;             if (mode == 0) { const float* xs = row < NPROMPT ? P.in[0] + (size_t)row * 1024 : P.in[1] + (size_t)(row - NPROMPT) * 1024;
; #pragma unroll
;                 for (int i = 0; i < 4; ++i) xv[r][i] = *(const f32x4*)(xs + (i * 64 + lane) * 4);
;             } else {
; #pragma unroll
;                 for (int i = 0; i < 4; ++i) { const u32x2 xw = __builtin_nontemporal_load((const u32x2*)(X16 + (size_t)row * 1024 + (i * 64 + lane) * 4)); const f32x2 a = unh2(xw.x), c = unh2(xw.y); xv[r][i] = (f32x4){a.x, a.y, c.x, c.y}; }
;                 sq[r] = lane < 16 ? ssq_t[row * 16 + lane] : 0.f;
; #pragma unroll
;                 for (int i = 0; i < 4; ++i) tw[r][i] = __builtin_nontemporal_load((const u32x2*)(T + (size_t)row * 1024 + (i * 64 + lane) * 4)); }
;             if (mode == 2) { const float* pp = row < NPROMPT ? P.in[2] + ((size_t)layer * NPROMPT + row) * 256 : P.in[3] + ((size_t)layer * (MTOK - NPROMPT) + (row - NPROMPT)) * 256;
;                 pv[r] = *(const f32x4*)(pp + lane * 4); } } }
; #pragma unroll
;         for (int r = 0; r < RU; ++r) { const int rrow = row0 + r * nw; const int row = rev ? MTOK - 1 - rrow : rrow; if (rrow < MTOK) {
;             if (mode != 0) { const float rs = rsqrtf(wave_sum(sq[r]) * (1.0f / 1024.0f) + EPSN);
; #pragma unroll
;                 for (int i = 0; i < 4; ++i) { const f32x4 g4 = *(const f32x4*)(gain + (i * 64 + lane) * 4);
.LBB0_1743:
	v_and_b32_e32 v66, 63, v1
	v_add_u32_e32 v1, 64, v148
	v_cmp_lt_i32_e32 vcc, v147, v1
	v_readlane_b32 s36, v238, 1
	s_lshl_b32 s16, s5, 3
	v_cndmask_b32_e32 v2, v184, v147, vcc
	v_cmp_lt_i32_e32 vcc, v146, v1
	s_lshl_b64 s[12:13], s[8:9], 2
	v_readlane_b32 s46, v238, 11
	v_lshlrev_b32_e32 v67, 2, v2
	v_cndmask_b32_e32 v2, v184, v146, vcc
	v_cmp_lt_i32_e32 vcc, v145, v1
	v_readlane_b32 s47, v238, 12
	s_add_u32 s12, s46, s12
	v_lshlrev_b32_e32 v68, 2, v2
	v_cndmask_b32_e32 v2, v184, v145, vcc
	v_cmp_lt_i32_e32 vcc, v144, v1
	s_addc_u32 s13, s47, s13
	v_lshlrev_b32_e32 v166, 4, v66
	v_lshlrev_b32_e32 v69, 2, v2
	v_cndmask_b32_e32 v2, v184, v144, vcc
	v_cmp_lt_i32_e32 vcc, v143, v1
	v_readlane_b32 s42, v238, 7
	v_readlane_b32 s43, v238, 8
	v_readlane_b32 s44, v238, 9
	v_readlane_b32 s45, v238, 10
	v_readlane_b32 s48, v238, 13
	v_readlane_b32 s49, v238, 14
	v_lshl_add_u64 v[32:33], s[12:13], 0, v[166:167]
	global_load_dwordx4 v[240:243], v[32:33], off
	global_load_dwordx4 v[244:247], v[32:33], off offset:1024
	global_load_dwordx4 v[248:251], v[32:33], off offset:2048
	global_load_dwordx4 v[252:255], v[32:33], off offset:3072
	v_lshlrev_b32_e32 v70, 2, v2
	v_cndmask_b32_e32 v2, v184, v143, vcc
	v_cmp_lt_i32_e32 vcc, v142, v1
	v_readlane_b32 s12, v238, 19
	v_readlane_b32 s38, v238, 3
	v_readlane_b32 s39, v238, 4
	v_readlane_b32 s42, v236, 23
	v_cndmask_b32_e32 v1, v184, v142, vcc
	v_lshl_add_u64 v[34:35], s[48:49], 0, v[166:167]
	v_lshlrev_b32_e32 v166, 3, v66
	v_readlane_b32 s13, v238, 20
	v_readlane_b32 s18, v236, 33
	v_readlane_b32 s46, v236, 27
	v_readlane_b32 s44, v236, 25
	v_add_u32_e32 v0, s4, v0
	v_readlane_b32 s43, v236, 24
	v_readlane_b32 s33, v236, 20
	v_cmp_gt_u32_e64 s[38:39], 16, v66
	v_lshlrev_b32_e32 v71, 2, v2
	v_lshlrev_b32_e32 v72, 2, v1
	v_lshl_add_u64 v[36:37], s[12:13], 0, v[166:167]
	v_lshl_add_u64 v[38:39], s[2:3], 0, v[166:167]
	v_lshl_add_u64 v[40:41], s[48:49], 0, v[166:167]
	v_readlane_b32 s19, v236, 34
	v_readlane_b32 s47, v236, 28
	v_readlane_b32 s45, v236, 26
	s_sub_i32 s0, 0, s16
	v_sub_u32_e32 v73, 0xbfff, v0
	s_lshl_b32 s8, s5, 4
	s_mov_b64 s[2:3], 0
	v_mov_b64_e32 v[42:43], v[166:167]
	v_readlane_b32 s37, v238, 2
	v_readlane_b32 s40, v238, 5
	v_readlane_b32 s41, v238, 6
	v_readlane_b32 s50, v238, 15
	v_readlane_b32 s51, v238, 16
	s_branch .LBB0_1745

; DI unsigned pk2(float a, float b) { f32x2 v = {a, b}; return __builtin_bit_cast(unsigned, __builtin_convertvector(v, bf2_t)); }
; DI float blo(unsigned w) { return __uint_as_float(w << 16); }
; DI float bhi(unsigned w) { return __uint_as_float(w & 0xffff0000u); }
; DI float wave_sum(float v) { for (int o = 32; o >= 1; o >>= 1) v += __shfl_xor(v, o); return v; }
; DI unsigned pkh2(float a, float b) { f32x2 v = {a, b}; return __builtin_bit_cast(unsigned, __builtin_convertvector(v, h2_t)); }
;     ...
;         for (int r = 0; r < RU; ++r) { const int rrow = row0 + r * nw; const int row = rev ? MTOK - 1 - rrow : rrow; if (rrow < MTOK) {
;             if (mode != 0) { const float rs = rsqrtf(wave_sum(sq[r]) * (1.0f / 1024.0f) + EPSN);
; #pragma unroll
;                 for (int i = 0; i < 4; ++i) { const f32x4 g4 = *(const f32x4*)(gain + (i * 64 + lane) * 4);
;                     xv[r][i][0] += blo(tw[r][i].x) * rs * g4[0]; xv[r][i][1] += bhi(tw[r][i].x) * rs * g4[1]; xv[r][i][2] += blo(tw[r][i].y) * rs * g4[2]; xv[r][i][3] += bhi(tw[r][i].y) * rs * g4[3]; } }
;             if (fin) {
; #pragma unroll
;                 for (int i = 0; i < 4; ++i) *(f32x4*)(P.out + (size_t)row * 1024 + (i * 64 + lane) * 4) = xv[r][i];
;             } else {
;                 float ss = 0.f;
; #pragma unroll
;                 for (int i = 0; i < 4; ++i) ss += xv[r][i][0] * xv[r][i][0] + xv[r][i][1] * xv[r][i][1] + xv[r][i][2] * xv[r][i][2] + xv[r][i][3] * xv[r][i][3];
;                 ss = wave_sum(ss);
;                 const float rx = norm_out ? rsqrtf(ss * (1.0f / 1024.0f) + EPSN) : 1.0f;
; #pragma unroll
;                 for (int i = 0; i < 4; ++i) { u32x2 xw; xw.x = pkh2(xv[r][i][0], xv[r][i][1]); xw.y = pkh2(xv[r][i][2], xv[r][i][3]);
;                     __builtin_nontemporal_store(xw, (u32x2*)(X16 + (size_t)row * 1024 + (i * 64 + lane) * 4));
;                     u32x2 w; w.x = pk2(xv[r][i][0] * rx, xv[r][i][1] * rx); w.y = pk2(xv[r][i][2] * rx, xv[r][i][3] * rx);
;                     *(u32x2*)(out2 + (size_t)row * 1024 + (i * 64 + lane) * 4) = w; }
.LBB0_1751:
	s_or_b64 exec, exec, s[12:13]
	global_load_dwordx4 v[74:77], v[32:33], off
	s_waitcnt vmcnt(8)
	v_cvt_f32_f16_sdwa v79, v28 dst_sel:DWORD dst_unused:UNUSED_PAD src0_sel:WORD_1
	v_cvt_f32_f16_e32 v78, v28
	v_cvt_f32_f16_sdwa v81, v29 dst_sel:DWORD dst_unused:UNUSED_PAD src0_sel:WORD_1
	v_cvt_f32_f16_e32 v80, v29
	s_waitcnt vmcnt(5)
	v_cvt_f32_f16_sdwa v29, v16 dst_sel:DWORD dst_unused:UNUSED_PAD src0_sel:WORD_1
	v_cvt_f32_f16_e32 v28, v16
	ds_bpermute_b32 v16, v67, v42
	v_cvt_f32_f16_sdwa v63, v17 dst_sel:DWORD dst_unused:UNUSED_PAD src0_sel:WORD_1
	v_cvt_f32_f16_e32 v62, v17
	s_mov_b32 s4, 0x800000
	v_cvt_f32_f16_sdwa v83, v24 dst_sel:DWORD dst_unused:UNUSED_PAD src0_sel:WORD_1
	s_waitcnt lgkmcnt(0)
	v_add_f32_e32 v16, v42, v16
	ds_bpermute_b32 v17, v68, v16
	v_cvt_f32_f16_e32 v82, v24
	v_cvt_f32_f16_sdwa v85, v25 dst_sel:DWORD dst_unused:UNUSED_PAD src0_sel:WORD_1
	v_cvt_f32_f16_e32 v84, v25
	v_cvt_f32_f16_sdwa v25, v20 dst_sel:DWORD dst_unused:UNUSED_PAD src0_sel:WORD_1
	s_waitcnt lgkmcnt(0)
	v_add_f32_e32 v16, v16, v17
	ds_bpermute_b32 v17, v69, v16
	v_cvt_f32_f16_e32 v24, v20
	v_cvt_f32_f16_sdwa v65, v21 dst_sel:DWORD dst_unused:UNUSED_PAD src0_sel:WORD_1
	v_cvt_f32_f16_e32 v64, v21
	s_waitcnt vmcnt(3)
	v_lshlrev_b32_e32 v20, 16, v22
	s_waitcnt lgkmcnt(0)
	v_add_f32_e32 v16, v16, v17
	ds_bpermute_b32 v17, v70, v16
	v_and_b32_e32 v21, 0xffff0000, v22
	v_lshlrev_b32_e32 v22, 16, v23
	v_and_b32_e32 v23, 0xffff0000, v23
	s_mov_b64 s[12:13], -1
	s_waitcnt lgkmcnt(0)
	v_add_f32_e32 v16, v16, v17
	ds_bpermute_b32 v17, v71, v16
	s_waitcnt lgkmcnt(0)
	v_add_f32_e32 v16, v16, v17
	ds_bpermute_b32 v17, v72, v16
	s_waitcnt lgkmcnt(0)
	v_add_f32_e32 v16, v16, v17
	v_fmamk_f32 v16, v16, 0x3a800000, v168
	v_cmp_gt_f32_e32 vcc, s4, v16
	v_mul_f32_e32 v17, 0x4b800000, v16
	s_nop 0
	v_cndmask_b32_e32 v16, v16, v17, vcc
	v_rsq_f32_e32 v16, v16
	s_nop 0
	v_mul_f32_e32 v17, 0x45800000, v16
	v_cndmask_b32_e32 v42, v16, v17, vcc
	v_lshlrev_b32_e32 v16, 16, v18
	v_and_b32_e32 v17, 0xffff0000, v18
	v_lshlrev_b32_e32 v18, 16, v19
	v_and_b32_e32 v19, 0xffff0000, v19
	v_pk_mul_f32 v[16:17], v[42:43], v[16:17] op_sel_hi:[0,1]
	v_pk_mul_f32 v[18:19], v[42:43], v[18:19] op_sel_hi:[0,1]
	v_pk_mul_f32 v[20:21], v[42:43], v[20:21] op_sel_hi:[0,1]
	v_pk_mul_f32 v[22:23], v[42:43], v[22:23] op_sel_hi:[0,1]
	s_and_b64 vcc, exec, s[18:19]
	s_waitcnt vmcnt(0)
	v_pk_fma_f32 v[16:17], v[74:75], v[16:17], v[78:79]
	v_pk_fma_f32 v[18:19], v[76:77], v[18:19], v[80:81]
	s_nop 1
	v_mov_b32_e32 v74, v244
	v_mov_b32_e32 v75, v245
	v_mov_b32_e32 v76, v246
	v_mov_b32_e32 v77, v247
	v_lshlrev_b32_e32 v78, 16, v26
	v_and_b32_e32 v79, 0xffff0000, v26
	v_lshlrev_b32_e32 v26, 16, v27
	v_and_b32_e32 v27, 0xffff0000, v27
	v_pk_mul_f32 v[78:79], v[42:43], v[78:79] op_sel_hi:[0,1]
	v_pk_mul_f32 v[26:27], v[42:43], v[26:27] op_sel_hi:[0,1]
	v_pk_fma_f32 v[20:21], v[74:75], v[20:21], v[82:83]
	v_pk_fma_f32 v[22:23], v[76:77], v[22:23], v[84:85]
	s_nop 1
	v_mov_b32_e32 v74, v248
	v_mov_b32_e32 v75, v249
	v_mov_b32_e32 v76, v250
	v_mov_b32_e32 v77, v251
	v_pk_fma_f32 v[24:25], v[74:75], v[78:79], v[24:25]
	v_pk_fma_f32 v[26:27], v[76:77], v[26:27], v[64:65]
	s_nop 1
	v_mov_b32_e32 v74, v252
	v_mov_b32_e32 v75, v253
	v_mov_b32_e32 v76, v254
	v_mov_b32_e32 v77, v255
	v_lshlrev_b32_e32 v64, 16, v30
	v_and_b32_e32 v65, 0xffff0000, v30
	v_lshlrev_b32_e32 v30, 16, v31
	v_and_b32_e32 v31, 0xffff0000, v31
	v_pk_mul_f32 v[64:65], v[42:43], v[64:65] op_sel_hi:[0,1]
	v_pk_mul_f32 v[30:31], v[42:43], v[30:31] op_sel_hi:[0,1]
	v_pk_fma_f32 v[28:29], v[74:75], v[64:65], v[28:29]
	v_pk_fma_f32 v[30:31], v[76:77], v[30:31], v[62:63]
	s_cbranch_vccz .LBB0_1754
	v_mov_b32_e32 v64, v17
	v_mov_b32_e32 v65, v21
	v_mov_b32_e32 v62, v16
	v_mov_b32_e32 v63, v20
	v_pk_mul_f32 v[64:65], v[64:65], v[64:65]
	v_mov_b32_e32 v74, v29
	v_pk_fma_f32 v[62:63], v[62:63], v[62:63], v[64:65]
	v_mov_b32_e32 v64, v18
	v_mov_b32_e32 v65, v22
	v_pk_fma_f32 v[62:63], v[64:65], v[64:65], v[62:63]
	v_mov_b32_e32 v64, v19
	v_mov_b32_e32 v65, v23
	v_mov_b32_e32 v75, v25
	v_pk_fma_f32 v[62:63], v[64:65], v[64:65], v[62:63]
	v_mov_b32_e32 v64, v28
	v_mov_b32_e32 v65, v24
	v_pk_mul_f32 v[74:75], v[74:75], v[74:75]
	v_add_f32_e32 v42, v62, v63
	v_pk_fma_f32 v[64:65], v[64:65], v[64:65], v[74:75]
	v_mov_b32_e32 v74, v30
	v_mov_b32_e32 v75, v26
	v_pk_fma_f32 v[64:65], v[74:75], v[74:75], v[64:65]
	v_mov_b32_e32 v74, v31
	v_mov_b32_e32 v75, v27
	v_pk_fma_f32 v[64:65], v[74:75], v[74:75], v[64:65]
	v_cvt_pk_f16_f32 v62, v16, v17
	v_add_f32_e32 v42, v65, v42
	v_add_f32_e32 v42, v64, v42
	ds_bpermute_b32 v53, v67, v42
	v_cvt_pk_f16_f32 v63, v18, v19
	global_store_dwordx2 v[58:59], v[62:63], off nt
	v_lshl_add_u64 v[60:61], v[40:41], 0, v[60:61]
	s_waitcnt lgkmcnt(0)
	v_add_f32_e32 v42, v42, v53
	ds_bpermute_b32 v53, v68, v42
	s_waitcnt lgkmcnt(0)
	v_add_f32_e32 v42, v42, v53
	ds_bpermute_b32 v53, v69, v42
	s_waitcnt lgkmcnt(0)
	v_add_f32_e32 v42, v42, v53
	ds_bpermute_b32 v53, v70, v42
	s_waitcnt lgkmcnt(0)
	v_add_f32_e32 v42, v42, v53
	ds_bpermute_b32 v53, v71, v42
	s_waitcnt lgkmcnt(0)
	v_add_f32_e32 v42, v42, v53
	ds_bpermute_b32 v53, v72, v42
	s_waitcnt lgkmcnt(0)
	v_add_f32_e32 v42, v42, v53
	v_fmamk_f32 v42, v42, 0x3a800000, v168
	v_cmp_gt_f32_e32 vcc, s4, v42
	v_mul_f32_e32 v53, 0x4b800000, v42
	s_nop 0
	v_cndmask_b32_e32 v42, v42, v53, vcc
	v_rsq_f32_e32 v42, v42
	s_nop 0
	v_mul_f32_e32 v53, 0x45800000, v42
	v_cndmask_b32_e32 v42, v42, v53, vcc
	v_pk_mul_f32 v[62:63], v[16:17], v[42:43] op_sel_hi:[1,0]
	v_pk_mul_f32 v[64:65], v[18:19], v[42:43] op_sel_hi:[1,0]
	v_cvt_pk_bf16_f32 v62, v62, v63
	v_cvt_pk_bf16_f32 v63, v64, v65
	global_store_dwordx2 v[60:61], v[62:63], off
	v_cvt_pk_f16_f32 v62, v20, v21
	v_cvt_pk_f16_f32 v63, v22, v23
	global_store_dwordx2 v[58:59], v[62:63], off offset:512 nt
	v_pk_mul_f32 v[62:63], v[20:21], v[42:43] op_sel_hi:[1,0]
	v_pk_mul_f32 v[64:65], v[22:23], v[42:43] op_sel_hi:[1,0]
	v_cvt_pk_bf16_f32 v62, v62, v63
	v_cvt_pk_bf16_f32 v63, v64, v65
	global_store_dwordx2 v[60:61], v[62:63], off offset:512
	v_cvt_pk_f16_f32 v62, v24, v25
	v_cvt_pk_f16_f32 v63, v26, v27
	global_store_dwordx2 v[58:59], v[62:63], off offset:1024 nt
	v_pk_mul_f32 v[62:63], v[24:25], v[42:43] op_sel_hi:[1,0]
	v_pk_mul_f32 v[64:65], v[26:27], v[42:43] op_sel_hi:[1,0]
	v_cvt_pk_bf16_f32 v62, v62, v63
	v_cvt_pk_bf16_f32 v63, v64, v65
	global_store_dwordx2 v[60:61], v[62:63], off offset:1024
	v_cvt_pk_f16_f32 v62, v28, v29
	v_cvt_pk_f16_f32 v63, v30, v31
	global_store_dwordx2 v[58:59], v[62:63], off offset:1536 nt
	v_pk_mul_f32 v[58:59], v[28:29], v[42:43] op_sel_hi:[1,0]
	v_pk_mul_f32 v[62:63], v[30:31], v[42:43] op_sel_hi:[1,0]
	v_cvt_pk_bf16_f32 v58, v58, v59
	v_cvt_pk_bf16_f32 v59, v62, v63
	global_store_dwordx2 v[60:61], v[58:59], off offset:1536
	s_cbranch_execz .LBB0_1755

; DI unsigned pk2(float a, float b) { f32x2 v = {a, b}; return __builtin_bit_cast(unsigned, __builtin_convertvector(v, bf2_t)); }
; DI float blo(unsigned w) { return __uint_as_float(w << 16); }
; DI float bhi(unsigned w) { return __uint_as_float(w & 0xffff0000u); }
; DI float wave_sum(float v) { for (int o = 32; o >= 1; o >>= 1) v += __shfl_xor(v, o); return v; }
; DI unsigned pkh2(float a, float b) { f32x2 v = {a, b}; return __builtin_bit_cast(unsigned, __builtin_convertvector(v, h2_t)); }
;     ...
;         for (int r = 0; r < RU; ++r) { const int rrow = row0 + r * nw; const int row = rev ? MTOK - 1 - rrow : rrow; if (rrow < MTOK) {
;             if (mode != 0) { const float rs = rsqrtf(wave_sum(sq[r]) * (1.0f / 1024.0f) + EPSN);
; #pragma unroll
;                 for (int i = 0; i < 4; ++i) { const f32x4 g4 = *(const f32x4*)(gain + (i * 64 + lane) * 4);
;                     xv[r][i][0] += blo(tw[r][i].x) * rs * g4[0]; xv[r][i][1] += bhi(tw[r][i].x) * rs * g4[1]; xv[r][i][2] += blo(tw[r][i].y) * rs * g4[2]; xv[r][i][3] += bhi(tw[r][i].y) * rs * g4[3]; } }
;             if (fin) {
; #pragma unroll
;                 for (int i = 0; i < 4; ++i) *(f32x4*)(P.out + (size_t)row * 1024 + (i * 64 + lane) * 4) = xv[r][i];
;             } else {
;                 float ss = 0.f;
; #pragma unroll
;                 for (int i = 0; i < 4; ++i) ss += xv[r][i][0] * xv[r][i][0] + xv[r][i][1] * xv[r][i][1] + xv[r][i][2] * xv[r][i][2] + xv[r][i][3] * xv[r][i][3];
;                 ss = wave_sum(ss);
;                 const float rx = norm_out ? rsqrtf(ss * (1.0f / 1024.0f) + EPSN) : 1.0f;
; #pragma unroll
;                 for (int i = 0; i < 4; ++i) { u32x2 xw; xw.x = pkh2(xv[r][i][0], xv[r][i][1]); xw.y = pkh2(xv[r][i][2], xv[r][i][3]);
;                     __builtin_nontemporal_store(xw, (u32x2*)(X16 + (size_t)row * 1024 + (i * 64 + lane) * 4));
;                     u32x2 w; w.x = pk2(xv[r][i][0] * rx, xv[r][i][1] * rx); w.y = pk2(xv[r][i][2] * rx, xv[r][i][3] * rx);
;                     *(u32x2*)(out2 + (size_t)row * 1024 + (i * 64 + lane) * 4) = w; }
.LBB0_1756:
	s_nop 1
	v_mov_b32_e32 v18, v240
	v_mov_b32_e32 v19, v241
	v_mov_b32_e32 v20, v242
	v_mov_b32_e32 v21, v243
	ds_bpermute_b32 v16, v67, v43
	v_lshlrev_b32_e32 v22, 16, v44
	v_and_b32_e32 v23, 0xffff0000, v44
	s_mov_b64 s[14:15], -1
	s_waitcnt lgkmcnt(0)
	v_add_f32_e32 v16, v43, v16
	ds_bpermute_b32 v17, v68, v16
	s_waitcnt lgkmcnt(0)
	v_add_f32_e32 v16, v16, v17
	ds_bpermute_b32 v17, v69, v16
	s_waitcnt lgkmcnt(0)
	v_add_f32_e32 v16, v16, v17
	ds_bpermute_b32 v17, v70, v16
	s_waitcnt lgkmcnt(0)
	v_add_f32_e32 v16, v16, v17
	ds_bpermute_b32 v17, v71, v16
	s_waitcnt lgkmcnt(0)
	v_add_f32_e32 v16, v16, v17
	ds_bpermute_b32 v17, v72, v16
	s_waitcnt lgkmcnt(0)
	v_add_f32_e32 v16, v16, v17
	v_fmamk_f32 v16, v16, 0x3a800000, v168
	v_cmp_gt_f32_e32 vcc, s4, v16
	v_mul_f32_e32 v17, 0x4b800000, v16
	s_nop 0
	v_cndmask_b32_e32 v16, v16, v17, vcc
	v_rsq_f32_e32 v16, v16
	s_nop 0
	v_mul_f32_e32 v17, 0x45800000, v16
	v_cndmask_b32_e32 v16, v16, v17, vcc
	v_pk_mul_f32 v[22:23], v[16:17], v[22:23] op_sel_hi:[0,1]
	s_and_b64 vcc, exec, s[18:19]
	v_pk_fma_f32 v[12:13], v[18:19], v[22:23], v[12:13]
	v_lshlrev_b32_e32 v18, 16, v45
	v_and_b32_e32 v19, 0xffff0000, v45
	v_pk_mul_f32 v[18:19], v[16:17], v[18:19] op_sel_hi:[0,1]
	v_pk_fma_f32 v[14:15], v[20:21], v[18:19], v[14:15]
	s_nop 1
	v_mov_b32_e32 v18, v244
	v_mov_b32_e32 v19, v245
	v_mov_b32_e32 v20, v246
	v_mov_b32_e32 v21, v247
	v_lshlrev_b32_e32 v22, 16, v46
	v_and_b32_e32 v23, 0xffff0000, v46
	v_pk_mul_f32 v[22:23], v[16:17], v[22:23] op_sel_hi:[0,1]
	v_pk_fma_f32 v[8:9], v[18:19], v[22:23], v[8:9]
	v_lshlrev_b32_e32 v18, 16, v47
	v_and_b32_e32 v19, 0xffff0000, v47
	v_pk_mul_f32 v[18:19], v[16:17], v[18:19] op_sel_hi:[0,1]
	v_pk_fma_f32 v[10:11], v[20:21], v[18:19], v[10:11]
	s_nop 1
	v_mov_b32_e32 v18, v248
	v_mov_b32_e32 v19, v249
	v_mov_b32_e32 v20, v250
	v_mov_b32_e32 v21, v251
	v_lshlrev_b32_e32 v22, 16, v48
	v_and_b32_e32 v23, 0xffff0000, v48
	v_pk_mul_f32 v[22:23], v[16:17], v[22:23] op_sel_hi:[0,1]
	v_pk_fma_f32 v[4:5], v[18:19], v[22:23], v[4:5]
	v_lshlrev_b32_e32 v18, 16, v49
	v_and_b32_e32 v19, 0xffff0000, v49
	v_pk_mul_f32 v[18:19], v[16:17], v[18:19] op_sel_hi:[0,1]
	v_pk_fma_f32 v[6:7], v[20:21], v[18:19], v[6:7]
	s_nop 1
	v_mov_b32_e32 v18, v252
	v_mov_b32_e32 v19, v253
	v_mov_b32_e32 v20, v254
	v_mov_b32_e32 v21, v255
	v_lshlrev_b32_e32 v22, 16, v50
	v_and_b32_e32 v23, 0xffff0000, v50
	v_pk_mul_f32 v[22:23], v[16:17], v[22:23] op_sel_hi:[0,1]
	v_pk_fma_f32 v[0:1], v[18:19], v[22:23], v[0:1]
	v_lshlrev_b32_e32 v18, 16, v51
	v_and_b32_e32 v19, 0xffff0000, v51
	v_pk_mul_f32 v[16:17], v[16:17], v[18:19] op_sel_hi:[0,1]
	v_pk_fma_f32 v[2:3], v[20:21], v[16:17], v[2:3]
	s_cbranch_vccz .LBB0_1758
	v_mov_b32_e32 v18, v13
	v_mov_b32_e32 v19, v9
	v_mov_b32_e32 v16, v12
	v_mov_b32_e32 v17, v8
	v_pk_mul_f32 v[18:19], v[18:19], v[18:19]
	v_mov_b32_e32 v20, v1
	v_pk_fma_f32 v[16:17], v[16:17], v[16:17], v[18:19]
	v_mov_b32_e32 v18, v14
	v_mov_b32_e32 v19, v10
	v_pk_fma_f32 v[16:17], v[18:19], v[18:19], v[16:17]
	v_mov_b32_e32 v18, v15
	v_mov_b32_e32 v19, v11
	v_mov_b32_e32 v21, v5
	v_pk_fma_f32 v[16:17], v[18:19], v[18:19], v[16:17]
	v_mov_b32_e32 v18, v0
	v_mov_b32_e32 v19, v4
	v_pk_mul_f32 v[20:21], v[20:21], v[20:21]
	v_add_f32_e32 v16, v16, v17
	v_pk_fma_f32 v[18:19], v[18:19], v[18:19], v[20:21]
	v_mov_b32_e32 v20, v2
	v_mov_b32_e32 v21, v6
	v_pk_fma_f32 v[18:19], v[20:21], v[20:21], v[18:19]
	v_mov_b32_e32 v20, v3
	v_mov_b32_e32 v21, v7
	v_pk_fma_f32 v[18:19], v[20:21], v[20:21], v[18:19]
	v_ashrrev_i32_e32 v55, 31, v54
	v_add_f32_e32 v16, v19, v16
	v_add_f32_e32 v16, v18, v16
	ds_bpermute_b32 v17, v67, v16
	v_lshlrev_b64 v[20:21], 11, v[54:55]
	v_cvt_pk_f16_f32 v18, v12, v13
	v_cvt_pk_f16_f32 v19, v14, v15
	v_lshl_add_u64 v[22:23], v[36:37], 0, v[20:21]
	s_waitcnt lgkmcnt(0)
	v_add_f32_e32 v16, v16, v17
	ds_bpermute_b32 v17, v68, v16
	global_store_dwordx2 v[22:23], v[18:19], off nt
	v_lshl_add_u64 v[20:21], v[40:41], 0, v[20:21]
	s_mov_b64 s[14:15], 0
	s_waitcnt lgkmcnt(0)
	v_add_f32_e32 v16, v16, v17
	ds_bpermute_b32 v17, v69, v16
	s_waitcnt lgkmcnt(0)
	v_add_f32_e32 v16, v16, v17
	ds_bpermute_b32 v17, v70, v16
	s_waitcnt lgkmcnt(0)
	v_add_f32_e32 v16, v16, v17
	ds_bpermute_b32 v17, v71, v16
	s_waitcnt lgkmcnt(0)
	v_add_f32_e32 v16, v16, v17
	ds_bpermute_b32 v17, v72, v16
	s_waitcnt lgkmcnt(0)
	v_add_f32_e32 v16, v16, v17
	v_fmamk_f32 v16, v16, 0x3a800000, v168
	v_cmp_gt_f32_e32 vcc, s4, v16
	v_mul_f32_e32 v17, 0x4b800000, v16
	s_nop 0
	v_cndmask_b32_e32 v16, v16, v17, vcc
	v_rsq_f32_e32 v16, v16
	s_nop 0
	v_mul_f32_e32 v17, 0x45800000, v16
	v_cndmask_b32_e32 v16, v16, v17, vcc
	v_pk_mul_f32 v[18:19], v[12:13], v[16:17] op_sel_hi:[1,0]
	v_pk_mul_f32 v[24:25], v[14:15], v[16:17] op_sel_hi:[1,0]
	v_cvt_pk_bf16_f32 v18, v18, v19
	v_cvt_pk_bf16_f32 v19, v24, v25
	global_store_dwordx2 v[20:21], v[18:19], off
	v_cvt_pk_f16_f32 v18, v8, v9
	v_cvt_pk_f16_f32 v19, v10, v11
	global_store_dwordx2 v[22:23], v[18:19], off offset:512 nt
	v_pk_mul_f32 v[18:19], v[8:9], v[16:17] op_sel_hi:[1,0]
	v_pk_mul_f32 v[24:25], v[10:11], v[16:17] op_sel_hi:[1,0]
	v_cvt_pk_bf16_f32 v18, v18, v19
	v_cvt_pk_bf16_f32 v19, v24, v25
	global_store_dwordx2 v[20:21], v[18:19], off offset:512
	v_cvt_pk_f16_f32 v18, v4, v5
	v_cvt_pk_f16_f32 v19, v6, v7
	global_store_dwordx2 v[22:23], v[18:19], off offset:1024 nt
	v_pk_mul_f32 v[18:19], v[4:5], v[16:17] op_sel_hi:[1,0]
	v_pk_mul_f32 v[24:25], v[6:7], v[16:17] op_sel_hi:[1,0]
	v_cvt_pk_bf16_f32 v18, v18, v19
	v_cvt_pk_bf16_f32 v19, v24, v25
	global_store_dwordx2 v[20:21], v[18:19], off offset:1024
	v_cvt_pk_f16_f32 v18, v0, v1
	v_cvt_pk_f16_f32 v19, v2, v3
	global_store_dwordx2 v[22:23], v[18:19], off offset:1536 nt
	v_pk_mul_f32 v[18:19], v[0:1], v[16:17] op_sel_hi:[1,0]
	v_pk_mul_f32 v[16:17], v[2:3], v[16:17] op_sel_hi:[1,0]
	v_cvt_pk_bf16_f32 v18, v18, v19
	v_cvt_pk_bf16_f32 v19, v16, v17
	global_store_dwordx2 v[20:21], v[18:19], off offset:1536
